# v12 + final-norm sample rows: both items of a thread in flight together, gains fetched before the wait for the tail tiles
# speedup vs baseline: 1.0063x; 1.0040x over previous
; __device__ __forceinline__ void phase8(const Params& p) {
;     const float* rsq = (const float*)(p.ws + WS_RSQ2); const float* g = p.in[24]; float* y = p.out; const bf16_t* xb = (const bf16_t*)(p.ws + WS_XB);
;     const long gtid = (long)blockIdx.x * NTHR + threadIdx.x, gsz = (long)gridDim.x * NTHR;
;     const long total = (long)T * 128;
;     for (long it = gtid; it < total; it += gsz) {
;         const long row = it >> 7; const int c8 = (int)(it & 127) * 8;
;         const float rs = rsqrtf(rsq[row] * (1.f / 1024.f) + EPS);
;         const u32x4 xw = *(const u32x4*)(xb + row * 1024 + c8);
;         const f32x4 g0 = *(const f32x4*)(g + c8), g1 = *(const f32x4*)(g + c8 + 4);
.Lp8_sample:
	v_readfirstlane_b32 s3, v28
	s_waitcnt vmcnt(0)
	s_lshl_b32 s6, s2, 9
	s_add_i32 s6, s6, 0x400000
	v_add_u32_e32 v0, s6, v28
	v_and_b32_e32 v5, 0x7f, v0
	v_lshrrev_b32_e32 v18, 7, v0
	v_lshlrev_b32_e32 v34, 5, v5
	global_load_dwordx4 v[10:13], v34, s[40:41]
	global_load_dwordx4 v[14:17], v34, s[40:41] offset:16
	v_lshlrev_b32_e32 v29, 2, v18
	v_add_u32_e32 v31, 0x1000, v29
	v_lshlrev_b32_e32 v32, 11, v18
	v_lshl_add_u32 v32, v5, 4, v32
	v_add_u32_e32 v33, 0x200000, v32
	v_lshlrev_b32_e32 v35, 12, v18
	v_add_u32_e32 v35, v35, v34
	v_add_u32_e32 v36, 0x400000, v35
	s_cmp_lt_u32 s3, 64
	s_cbranch_scc0 .Lp8_polled
	s_add_u32 s6, s44, 0x1f711900
	s_addc_u32 s7, s45, 0
	v_mov_b32_e32 v0, 0

; __device__ __forceinline__ float bflo(unsigned w) { return __uint_as_float(w << 16); }
; __device__ __forceinline__ float bfhi(unsigned w) { return __uint_as_float(w & 0xffff0000u); }
; __device__ __forceinline__ void phase8(const Params& p) {
;     ...
;     for (long it = gtid; it < total; it += gsz) {
;         const long row = it >> 7; const int c8 = (int)(it & 127) * 8;
;         const float rs = rsqrtf(rsq[row] * (1.f / 1024.f) + EPS);
;         const u32x4 xw = *(const u32x4*)(xb + row * 1024 + c8);
;         const f32x4 g0 = *(const f32x4*)(g + c8), g1 = *(const f32x4*)(g + c8 + 4);
;         f32x4 o0, o1;
;         o0[0] = bflo(xw.x) * rs * g0[0]; o0[1] = bfhi(xw.x) * rs * g0[1]; o0[2] = bflo(xw.y) * rs * g0[2]; o0[3] = bfhi(xw.y) * rs * g0[3];
;         o1[0] = bflo(xw.z) * rs * g1[0]; o1[1] = bfhi(xw.z) * rs * g1[1]; o1[2] = bflo(xw.w) * rs * g1[2]; o1[3] = bfhi(xw.w) * rs * g1[3];
;         *(f32x4*)(y + row * 1024 + c8) = o0; *(f32x4*)(y + row * 1024 + c8 + 4) = o1;
;     }
.Lp8_polled:
	s_barrier
	global_load_dword v40, v29, s[0:1]
	global_load_dword v41, v31, s[0:1]
	global_load_dwordx4 v[6:9], v32, s[4:5]
	global_load_dwordx4 v[44:47], v33, s[4:5]
	s_waitcnt vmcnt(0)
	v_fmamk_f32 v5, v40, 0x3a800000, v4
	v_mul_f32_e32 v20, 0x4b800000, v5
	v_cmp_gt_f32_e32 vcc, s12, v5
	v_and_b32_e32 v21, 0xffff0000, v6
	s_nop 0
	v_cndmask_b32_e32 v5, v5, v20, vcc
	v_rsq_f32_e32 v5, v5
	v_lshlrev_b32_e32 v20, 16, v6
	v_lshlrev_b32_e32 v6, 16, v7
	v_and_b32_e32 v7, 0xffff0000, v7
	v_mul_f32_e32 v24, 0x45800000, v5
	v_cndmask_b32_e32 v24, v5, v24, vcc
	v_lshlrev_b32_e32 v22, 16, v8
	v_and_b32_e32 v23, 0xffff0000, v8
	v_lshlrev_b32_e32 v8, 16, v9
	v_and_b32_e32 v9, 0xffff0000, v9
	v_pk_mul_f32 v[20:21], v[24:25], v[20:21] op_sel_hi:[0,1]
	v_pk_mul_f32 v[26:27], v[24:25], v[6:7] op_sel_hi:[0,1]
	v_pk_mul_f32 v[22:23], v[24:25], v[22:23] op_sel_hi:[0,1]
	v_pk_mul_f32 v[24:25], v[24:25], v[8:9] op_sel_hi:[0,1]
	v_pk_mul_f32 v[6:7], v[10:11], v[20:21]
	v_pk_mul_f32 v[8:9], v[12:13], v[26:27]
	v_pk_mul_f32 v[48:49], v[14:15], v[22:23]
	v_pk_mul_f32 v[50:51], v[16:17], v[24:25]
	global_store_dwordx4 v35, v[6:9], s[42:43]
	global_store_dwordx4 v35, v[48:51], s[42:43] offset:16
	v_fmamk_f32 v52, v41, 0x3a800000, v4
	v_mul_f32_e32 v54, 0x4b800000, v52
	v_cmp_gt_f32_e32 vcc, s12, v52
	v_and_b32_e32 v55, 0xffff0000, v44
	s_nop 0
	v_cndmask_b32_e32 v52, v52, v54, vcc
	v_rsq_f32_e32 v52, v52
	v_lshlrev_b32_e32 v54, 16, v44
	v_lshlrev_b32_e32 v44, 16, v45
	v_and_b32_e32 v45, 0xffff0000, v45
	v_mul_f32_e32 v58, 0x45800000, v52
	v_cndmask_b32_e32 v58, v52, v58, vcc
	v_lshlrev_b32_e32 v56, 16, v46
	v_and_b32_e32 v57, 0xffff0000, v46
	v_lshlrev_b32_e32 v46, 16, v47
	v_and_b32_e32 v47, 0xffff0000, v47
	v_pk_mul_f32 v[54:55], v[58:59], v[54:55] op_sel_hi:[0,1]
	v_pk_mul_f32 v[60:61], v[58:59], v[44:45] op_sel_hi:[0,1]
	v_pk_mul_f32 v[56:57], v[58:59], v[56:57] op_sel_hi:[0,1]
	v_pk_mul_f32 v[58:59], v[58:59], v[46:47] op_sel_hi:[0,1]
	v_pk_mul_f32 v[44:45], v[10:11], v[54:55]
	v_pk_mul_f32 v[46:47], v[12:13], v[60:61]
	v_pk_mul_f32 v[62:63], v[14:15], v[56:57]
	v_pk_mul_f32 v[64:65], v[16:17], v[58:59]
	global_store_dwordx4 v36, v[44:47], s[42:43]
	global_store_dwordx4 v36, v[62:65], s[42:43] offset:16
	s_branch .LBB0_1563
